# v12 + LRU-gate phase: all eight token-fragment loads and the four gate-input loads issued up front, second unrolled iteration prefetched behind the first epilogue
# speedup vs baseline: 1.0099x; 1.0046x over previous
; __global__ void __launch_bounds__(512, 2) fwd_kernel(Args args) {
;     ...
;         for (int it = vcu; it < 64 * 16; it += G) {
;             const int pm = it & 63, h = it >> 6;
;             bf16x8 wrf[8], wif[8];
;             { const bf16_t* wr_ = Wg + (size_t)(256 * h + 32 * cb + c) * 128 + 8 * hi2;
; #pragma unroll
;               for (int ks = 0; ks < 8; ++ks) { wrf[ks] = *(const bf16x8*)(wr_ + 16 * ks); wif[ks] = *(const bf16x8*)(wr_ + 128 * 128 + 16 * ks); } }
;             f32x4 br[4], bi[4], sp[4];
; #pragma unroll
;             for (int g = 0; g < 4; ++g) { const int ch = 128 * h + 32 * cb + 8 * g + 4 * hi2; br[g] = *(const f32x4*)(b_rg + ch); bi[g] = *(const f32x4*)(b_ig + ch); sp[g] = *(const f32x4*)(WSF(O_SPV) + ch); }
; #pragma unroll 2
;             for (int i = 0; i < 4; ++i) {
;                 const size_t tok = (size_t)pm * 256 + ((wave >> 2) + 2 * i) * 32 + c;
;                 bf16x8 xf[8];
; #pragma unroll
;                 for (int ks = 0; ks < 8; ++ks) xf[ks] = *(const bf16x8*)(xcb + tok * DM + 128 * h + 16 * ks + 8 * hi2);
;                 f32x16 ar, ai;
; #pragma unroll
;                 for (int r = 0; r < 16; ++r) { ar[r] = 0.f; ai[r] = 0.f; }
; #pragma unroll
;                 for (int ks = 0; ks < 8; ++ks) {
;                     ar = __builtin_amdgcn_mfma_f32_32x32x16_bf16(wrf[ks], xf[ks], ar, 0, 0, 0);
;                     ai = __builtin_amdgcn_mfma_f32_32x32x16_bf16(wif[ks], xf[ks], ai, 0, 0, 0);
;                 }
.LBB0_593:
	s_ashr_i32 s2, s15, 6
	v_lshl_or_b32 v0, s2, 8, v179
	v_ashrrev_i32_e32 v1, 31, v0
	v_lshlrev_b64 v[0:1], 8, v[0:1]
	v_lshl_add_u64 v[0:1], v[156:157], 0, v[0:1]
	v_add_co_u32_e32 v2, vcc, s12, v0
	s_lshl_b32 s2, s2, 7
	s_nop 0
	v_addc_co_u32_e32 v3, vcc, 0, v1, vcc
	global_load_dwordx4 v[34:37], v[0:1], off
	global_load_dwordx4 v[38:41], v[0:1], off offset:32
	global_load_dwordx4 v[42:45], v[2:3], off
	global_load_dwordx4 v[46:49], v[2:3], off offset:32
	global_load_dwordx4 v[50:53], v[0:1], off offset:64
	global_load_dwordx4 v[54:57], v[0:1], off offset:96
	global_load_dwordx4 v[58:61], v[2:3], off offset:64
	global_load_dwordx4 v[62:65], v[2:3], off offset:96
	global_load_dwordx4 v[66:69], v[0:1], off offset:128
	global_load_dwordx4 v[70:73], v[0:1], off offset:160
	global_load_dwordx4 v[74:77], v[2:3], off offset:128
	global_load_dwordx4 v[78:81], v[2:3], off offset:160
	global_load_dwordx4 v[82:85], v[0:1], off offset:192
	global_load_dwordx4 v[86:89], v[0:1], off offset:224
	global_load_dwordx4 v[90:93], v[2:3], off offset:192
	global_load_dwordx4 v[94:97], v[2:3], off offset:224
	v_or_b32_e32 v0, s2, v178
	v_readlane_b32 s16, v254, 20
	v_ashrrev_i32_e32 v1, 31, v0
	v_readlane_b32 s17, v254, 21
	v_readlane_b32 s24, v254, 28
	v_readlane_b32 s25, v254, 29
	v_lshlrev_b64 v[2:3], 2, v[0:1]
	v_readlane_b32 s20, v254, 24
	v_readlane_b32 s21, v254, 25
	v_readlane_b32 s28, v254, 32
	v_readlane_b32 s29, v254, 33
	s_mov_b64 s[16:17], s[24:25]
	v_or_b32_e32 v10, 8, v0
	s_mov_b64 s[20:21], s[28:29]
	v_lshl_add_u64 v[4:5], s[16:17], 0, v[2:3]
	s_waitcnt vmcnt(16)
	v_lshl_add_u64 v[8:9], s[4:5], 0, v[2:3]
	v_ashrrev_i32_e32 v11, 31, v10
	v_lshl_add_u64 v[6:7], s[20:21], 0, v[2:3]
	global_load_dwordx4 v[98:101], v[4:5], off
	global_load_dwordx4 v[102:105], v[4:5], off offset:32
	global_load_dwordx4 v[106:109], v[6:7], off
	global_load_dwordx4 v[110:113], v[6:7], off offset:32
	v_lshl_add_u64 v[10:11], v[10:11], 2, s[4:5]
	global_load_dwordx4 v[114:117], v[8:9], off
	global_load_dwordx4 v[118:121], v[10:11], off
	v_or_b32_e32 v8, 16, v0
	v_ashrrev_i32_e32 v9, 31, v8
	v_or_b32_e32 v10, 24, v0
	global_load_dwordx4 v[122:125], v[4:5], off offset:64
	global_load_dwordx4 v[126:129], v[4:5], off offset:96
	global_load_dwordx4 v[130:133], v[6:7], off offset:64
	global_load_dwordx4 v[134:137], v[6:7], off offset:96
	v_lshl_add_u64 v[8:9], v[8:9], 2, s[4:5]
	v_ashrrev_i32_e32 v11, 31, v10
	v_lshl_add_u64 v[4:5], v[10:11], 2, s[4:5]
	global_load_dwordx4 v[138:141], v[8:9], off
	global_load_dwordx4 v[142:145], v[4:5], off
	s_and_b32 s3, s10, 0x3f00
	v_add_u32_e32 v154, s3, v181
	v_lshlrev_b64 v[4:5], 13, v[154:155]
	v_lshlrev_b64 v[6:7], 12, v[154:155]
	v_add_u32_e32 v154, s3, v180
	v_lshlrev_b64 v[8:9], 12, v[154:155]
	s_ashr_i32 s3, s2, 31
	v_lshlrev_b64 v[0:1], 1, v[0:1]
	v_lshl_add_u64 v[162:163], v[6:7], 0, v[0:1]
	v_lshl_add_u64 v[164:165], v[8:9], 0, v[0:1]
	v_lshl_add_u64 v[0:1], v[158:159], 0, v[6:7]
	s_lshl_b64 s[2:3], s[2:3], 1
	v_lshlrev_b64 v[10:11], 13, v[154:155]
	v_lshl_add_u64 v[166:167], v[0:1], 0, s[2:3]
	v_lshl_add_u64 v[0:1], v[158:159], 0, v[8:9]
	v_lshl_add_u64 v[160:161], v[4:5], 0, v[2:3]
	v_lshl_add_u64 v[168:169], v[10:11], 0, v[2:3]
	v_lshl_add_u64 v[170:171], v[0:1], 0, s[2:3]
	s_mov_b32 s3, 4
	v_readlane_b32 s18, v254, 22
	v_readlane_b32 s19, v254, 23
	v_readlane_b32 s22, v254, 26
	v_readlane_b32 s23, v254, 27
	v_readlane_b32 s26, v254, 30
	v_readlane_b32 s27, v254, 31
	v_readlane_b32 s30, v254, 34
	v_readlane_b32 s31, v254, 35
	s_add_u32 s98, s96, s13
	s_addc_u32 s99, s97, 0
.LBB0_594:
	v_lshl_add_u64 v[0:1], s[96:97], 0, v[170:171]
	global_load_dwordx4 v[192:195], v[0:1], off offset:-128
	global_load_dwordx4 v[196:199], v[0:1], off offset:-96
	global_load_dwordx4 v[200:203], v[0:1], off offset:-64
	global_load_dwordx4 v[204:207], v[0:1], off offset:-32
	global_load_dwordx4 v[208:211], v[0:1], off offset:0
	global_load_dwordx4 v[212:215], v[0:1], off offset:32
	global_load_dwordx4 v[216:219], v[0:1], off offset:64
	global_load_dwordx4 v[220:223], v[0:1], off offset:96
	global_load_dwordx2 v[224:225], v164, s[98:99]
	global_load_dwordx2 v[226:227], v164, s[98:99] offset:16
	global_load_dwordx2 v[228:229], v164, s[98:99] offset:32
	global_load_dwordx2 v[230:231], v164, s[98:99] offset:48
	v_lshl_add_u64 v[174:175], s[96:97], 0, v[164:165]
	v_lshl_add_u64 v[176:177], s[96:97], 0, v[168:169]
	v_lshl_add_u64 v[172:173], s[96:97], 0, v[166:167]
	s_add_i32 s3, s3, -2
	v_lshl_add_u64 v[164:165], v[164:165], 0, s[8:9]
	v_lshl_add_u64 v[166:167], v[166:167], 0, s[8:9]
	v_lshl_add_u64 v[168:169], v[168:169], 0, s[6:7]
	v_lshl_add_u64 v[170:171], v[170:171], 0, s[8:9]
	s_cmp_eq_u32 s3, 0
	s_waitcnt vmcnt(11)
	v_mfma_f32_32x32x16_bf16 v[2:17], v[34:37], v[192:195], 0
	v_mfma_f32_32x32x16_bf16 v[18:33], v[42:45], v[192:195], 0
	s_waitcnt vmcnt(10)
	v_mfma_f32_32x32x16_bf16 v[2:17], v[38:41], v[196:199], v[2:17]
	v_mfma_f32_32x32x16_bf16 v[18:33], v[46:49], v[196:199], v[18:33]
	s_waitcnt vmcnt(9)
	v_mfma_f32_32x32x16_bf16 v[2:17], v[50:53], v[200:203], v[2:17]
	v_mfma_f32_32x32x16_bf16 v[18:33], v[58:61], v[200:203], v[18:33]
	s_waitcnt vmcnt(8)
	v_mfma_f32_32x32x16_bf16 v[2:17], v[54:57], v[204:207], v[2:17]
	v_mfma_f32_32x32x16_bf16 v[18:33], v[62:65], v[204:207], v[18:33]
	s_waitcnt vmcnt(7)
	v_mfma_f32_32x32x16_bf16 v[2:17], v[66:69], v[208:211], v[2:17]
	v_mfma_f32_32x32x16_bf16 v[18:33], v[74:77], v[208:211], v[18:33]
	s_waitcnt vmcnt(6)
	v_mfma_f32_32x32x16_bf16 v[2:17], v[70:73], v[212:215], v[2:17]
	v_mfma_f32_32x32x16_bf16 v[18:33], v[78:81], v[212:215], v[18:33]
	s_waitcnt vmcnt(5)
; DI unsigned pk2(float lo, float hi) { f32x2_t v = {lo, hi}; bf16x2_t b = __builtin_convertvector(v, bf16x2_t); return __builtin_bit_cast(unsigned, b); }
; DI float bflo(unsigned u) { return __uint_as_float(u << 16); }
; DI float bfhi(unsigned u) { return __uint_as_float(u & 0xffff0000u); }
; DI float sigm(float x) { return __builtin_amdgcn_rcpf(1.f + __builtin_amdgcn_exp2f(-1.4426950408889634f * x)); }
; __global__ void __launch_bounds__(512, 2) fwd_kernel(Args args) {
;     ...
;             for (int i = 0; i < 4; ++i) {
;                 const size_t tok = (size_t)pm * 256 + ((wave >> 2) + 2 * i) * 32 + c;
;                 bf16x8 xf[8];
; #pragma unroll
;                 for (int ks = 0; ks < 8; ++ks) xf[ks] = *(const bf16x8*)(xcb + tok * DM + 128 * h + 16 * ks + 8 * hi2);
;                 f32x16 ar, ai;
; #pragma unroll
;                 for (int r = 0; r < 16; ++r) { ar[r] = 0.f; ai[r] = 0.f; }
; #pragma unroll
;                 for (int ks = 0; ks < 8; ++ks) {
;                     ar = __builtin_amdgcn_mfma_f32_32x32x16_bf16(wrf[ks], xf[ks], ar, 0, 0, 0);
;                     ai = __builtin_amdgcn_mfma_f32_32x32x16_bf16(wif[ks], xf[ks], ai, 0, 0, 0);
;                 }
; #pragma unroll
;                 for (int g = 0; g < 4; ++g) {
;                     const int ch = 128 * h + 32 * cb + 8 * g + 4 * hi2;
;                     const u32x2 xv = *(const u32x2*)(xcb + tok * DM + ch);
;                     const float xx[4] = {bflo(xv.x), bfhi(xv.x), bflo(xv.y), bfhi(xv.y)};
;                     unsigned o[4];
; #pragma unroll
;                     for (int e = 0; e < 4; ++e) { const float r = sigm(ar[4 * g + e] + br[g][e]), ig = sigm(ai[4 * g + e] + bi[g][e]);
;                         const float oma = 1.f - __expf(r * sp[g][e]);
;                         o[e] = pk2(oma, __builtin_amdgcn_sqrtf(oma * (2.f - oma)) * ig * xx[e]); }
;                     *(u32x4*)(AU + tok * DM + ch) = (u32x4){o[0], o[1], o[2], o[3]};
	v_mfma_f32_32x32x16_bf16 v[2:17], v[82:85], v[216:219], v[2:17]
	v_mfma_f32_32x32x16_bf16 v[18:33], v[90:93], v[216:219], v[18:33]
	v_add_co_u32_e32 v152, vcc, s13, v174
	s_nop 1
	v_addc_co_u32_e32 v153, vcc, 0, v175, vcc
	v_add_co_u32_e32 v150, vcc, s14, v176
	s_waitcnt vmcnt(4)
	v_mfma_f32_32x32x16_bf16 v[2:17], v[86:89], v[220:223], v[2:17]
	v_addc_co_u32_e32 v151, vcc, 0, v177, vcc
	s_nop 10
	v_add_f32_e32 v2, v2, v98
	v_add_f32_e32 v3, v3, v99
	v_add_f32_e32 v4, v4, v100
	v_add_f32_e32 v5, v5, v101
	v_mul_f32_e32 v2, 0xbfb8aa3b, v2
	v_mul_f32_e32 v3, 0xbfb8aa3b, v3
	v_mul_f32_e32 v4, 0xbfb8aa3b, v4
	v_mul_f32_e32 v5, 0xbfb8aa3b, v5
	v_exp_f32_e32 v2, v2
	v_exp_f32_e32 v3, v3
	v_exp_f32_e32 v4, v4
	v_exp_f32_e32 v5, v5
	v_mfma_f32_32x32x16_bf16 v[18:33], v[94:97], v[220:223], v[18:33]
	global_load_dwordx4 v[192:195], v[172:173], off offset:-128
	global_load_dwordx4 v[196:199], v[172:173], off offset:-96
	global_load_dwordx4 v[200:203], v[172:173], off offset:-64
	global_load_dwordx4 v[204:207], v[172:173], off offset:-32
	global_load_dwordx4 v[208:211], v[172:173], off offset:0
	global_load_dwordx4 v[212:215], v[172:173], off offset:32
	global_load_dwordx4 v[216:219], v[172:173], off offset:64
	global_load_dwordx4 v[220:223], v[172:173], off offset:96
	global_load_dwordx2 v[232:233], v162, s[98:99]
	global_load_dwordx2 v[234:235], v162, s[98:99] offset:16
	global_load_dwordx2 v[236:237], v162, s[98:99] offset:32
	global_load_dwordx2 v[238:239], v162, s[98:99] offset:48
	v_add_f32_e32 v2, 1.0, v2
	v_add_f32_e32 v3, 1.0, v3
	v_add_f32_e32 v4, 1.0, v4
	v_add_f32_e32 v5, 1.0, v5
	v_rcp_f32_e32 v2, v2
	v_rcp_f32_e32 v3, v3
	v_rcp_f32_e32 v4, v4
	v_rcp_f32_e32 v5, v5
	v_mul_f32_e32 v2, v114, v2
	v_mul_f32_e32 v3, v115, v3
	v_mul_f32_e32 v4, v116, v4
	v_mul_f32_e32 v5, v117, v5
	v_mul_f32_e32 v2, 0x3fb8aa3b, v2
	v_mul_f32_e32 v3, 0x3fb8aa3b, v3
	v_mul_f32_e32 v4, 0x3fb8aa3b, v4
	v_mul_f32_e32 v5, 0x3fb8aa3b, v5
	v_add_f32_e32 v18, v18, v106
	v_add_f32_e32 v19, v19, v107
	v_add_f32_e32 v20, v20, v108
	v_add_f32_e32 v21, v21, v109
	v_exp_f32_e32 v2, v2
	v_exp_f32_e32 v3, v3
	v_exp_f32_e32 v4, v4
	v_exp_f32_e32 v5, v5
	v_mul_f32_e32 v18, 0xbfb8aa3b, v18
	v_mul_f32_e32 v19, 0xbfb8aa3b, v19
	v_mul_f32_e32 v20, 0xbfb8aa3b, v20
	v_mul_f32_e32 v21, 0xbfb8aa3b, v21
	v_exp_f32_e32 v18, v18
	v_exp_f32_e32 v19, v19
	v_exp_f32_e32 v20, v20
	v_exp_f32_e32 v21, v21
	v_sub_f32_e32 v2, 1.0, v2
	v_sub_f32_e32 v3, 1.0, v3
	v_sub_f32_e32 v4, 1.0, v4
	v_sub_f32_e32 v5, 1.0, v5
	v_sub_f32_e32 v146, 2.0, v2
	v_sub_f32_e32 v147, 2.0, v3
	v_sub_f32_e32 v148, 2.0, v4
	v_sub_f32_e32 v149, 2.0, v5
	v_add_f32_e32 v18, 1.0, v18
	v_add_f32_e32 v19, 1.0, v19
	v_add_f32_e32 v20, 1.0, v20
	v_add_f32_e32 v21, 1.0, v21
	v_mul_f32_e32 v146, v2, v146
	v_mul_f32_e32 v147, v3, v147
	v_mul_f32_e32 v148, v4, v148
	v_mul_f32_e32 v149, v5, v149
	v_rcp_f32_e32 v18, v18
	v_rcp_f32_e32 v19, v19
	v_rcp_f32_e32 v20, v20
	v_rcp_f32_e32 v21, v21
	v_sqrt_f32_e32 v146, v146
	v_sqrt_f32_e32 v147, v147
	v_sqrt_f32_e32 v148, v148
	v_sqrt_f32_e32 v149, v149
	s_waitcnt vmcnt(12)
	v_mov_b32_e32 v0, v224
	v_mov_b32_e32 v1, v225
	v_lshlrev_b32_e32 v154, 16, v0
	v_and_b32_e32 v0, 0xffff0000, v0
	v_lshlrev_b32_e32 v174, 16, v1
	v_and_b32_e32 v1, 0xffff0000, v1
	v_mul_f32_e32 v18, v18, v146
	v_mul_f32_e32 v19, v19, v147
	v_mul_f32_e32 v20, v20, v148
	v_mul_f32_e32 v21, v21, v149
	v_mul_f32_e32 v18, v18, v154
	v_mul_f32_e32 v0, v19, v0
	v_mul_f32_e32 v19, v20, v174
	v_mul_f32_e32 v1, v21, v1
	v_cvt_pk_bf16_f32 v2, v2, v18
	v_cvt_pk_bf16_f32 v3, v3, v0
	v_cvt_pk_bf16_f32 v4, v4, v19
	v_cvt_pk_bf16_f32 v5, v5, v1
	global_store_dwordx4 v[150:151], v[2:5], off
	v_mov_b32_e32 v0, v226
	v_mov_b32_e32 v1, v227
	v_add_f32_e32 v6, v6, v102
	v_add_f32_e32 v7, v7, v103
	v_add_f32_e32 v8, v8, v104
	v_add_f32_e32 v9, v9, v105
	v_mul_f32_e32 v6, 0xbfb8aa3b, v6
	v_mul_f32_e32 v7, 0xbfb8aa3b, v7
	v_mul_f32_e32 v8, 0xbfb8aa3b, v8
	v_mul_f32_e32 v9, 0xbfb8aa3b, v9
	v_exp_f32_e32 v6, v6
	v_exp_f32_e32 v7, v7
	v_exp_f32_e32 v8, v8
	v_exp_f32_e32 v9, v9
	v_add_f32_e32 v6, 1.0, v6
	v_add_f32_e32 v7, 1.0, v7
	v_add_f32_e32 v8, 1.0, v8
	v_add_f32_e32 v9, 1.0, v9
	v_rcp_f32_e32 v6, v6
	v_rcp_f32_e32 v7, v7
	v_rcp_f32_e32 v8, v8
	v_rcp_f32_e32 v9, v9
	v_mul_f32_e32 v6, v118, v6
	v_mul_f32_e32 v7, v119, v7
	v_mul_f32_e32 v8, v120, v8
	v_mul_f32_e32 v9, v121, v9
	v_mul_f32_e32 v6, 0x3fb8aa3b, v6
	v_mul_f32_e32 v7, 0x3fb8aa3b, v7
	v_mul_f32_e32 v8, 0x3fb8aa3b, v8
	v_mul_f32_e32 v9, 0x3fb8aa3b, v9
	v_add_f32_e32 v22, v22, v110
	v_add_f32_e32 v23, v23, v111
	v_add_f32_e32 v24, v24, v112
	v_add_f32_e32 v25, v25, v113
	v_exp_f32_e32 v6, v6
	v_exp_f32_e32 v7, v7
	v_exp_f32_e32 v8, v8
	v_exp_f32_e32 v9, v9
	v_mul_f32_e32 v22, 0xbfb8aa3b, v22
	v_mul_f32_e32 v23, 0xbfb8aa3b, v23
	v_mul_f32_e32 v24, 0xbfb8aa3b, v24
	v_mul_f32_e32 v25, 0xbfb8aa3b, v25
	v_exp_f32_e32 v22, v22
	v_exp_f32_e32 v23, v23
	v_exp_f32_e32 v24, v24
	v_exp_f32_e32 v25, v25
	v_sub_f32_e32 v6, 1.0, v6
	v_sub_f32_e32 v7, 1.0, v7
	v_sub_f32_e32 v8, 1.0, v8
	v_sub_f32_e32 v9, 1.0, v9
	v_sub_f32_e32 v175, 2.0, v6
	v_sub_f32_e32 v176, 2.0, v7
	v_sub_f32_e32 v177, 2.0, v8
	v_sub_f32_e32 v182, 2.0, v9
	v_add_f32_e32 v22, 1.0, v22
	v_add_f32_e32 v23, 1.0, v23
	v_add_f32_e32 v24, 1.0, v24
	v_add_f32_e32 v25, 1.0, v25
	v_mul_f32_e32 v175, v6, v175
	v_mul_f32_e32 v176, v7, v176
	v_mul_f32_e32 v177, v8, v177
	v_mul_f32_e32 v182, v9, v182
	v_rcp_f32_e32 v22, v22
	v_rcp_f32_e32 v23, v23
	v_rcp_f32_e32 v24, v24
	v_rcp_f32_e32 v25, v25
	v_sqrt_f32_e32 v175, v175
	v_sqrt_f32_e32 v176, v176
	v_sqrt_f32_e32 v177, v177
	v_sqrt_f32_e32 v182, v182
	v_mul_f32_e32 v22, v22, v175
; DI unsigned pk2(float lo, float hi) { f32x2_t v = {lo, hi}; bf16x2_t b = __builtin_convertvector(v, bf16x2_t); return __builtin_bit_cast(unsigned, b); }
; DI float bflo(unsigned u) { return __uint_as_float(u << 16); }
; DI float bfhi(unsigned u) { return __uint_as_float(u & 0xffff0000u); }
; DI float sigm(float x) { return __builtin_amdgcn_rcpf(1.f + __builtin_amdgcn_exp2f(-1.4426950408889634f * x)); }
; __global__ void __launch_bounds__(512, 2) fwd_kernel(Args args) {
;     ...
;                 for (int g = 0; g < 4; ++g) {
;                     const int ch = 128 * h + 32 * cb + 8 * g + 4 * hi2;
;                     const u32x2 xv = *(const u32x2*)(xcb + tok * DM + ch);
;                     const float xx[4] = {bflo(xv.x), bfhi(xv.x), bflo(xv.y), bfhi(xv.y)};
;                     unsigned o[4];
; #pragma unroll
;                     for (int e = 0; e < 4; ++e) { const float r = sigm(ar[4 * g + e] + br[g][e]), ig = sigm(ai[4 * g + e] + bi[g][e]);
;                         const float oma = 1.f - __expf(r * sp[g][e]);
;                         o[e] = pk2(oma, __builtin_amdgcn_sqrtf(oma * (2.f - oma)) * ig * xx[e]); }
;                     *(u32x4*)(AU + tok * DM + ch) = (u32x4){o[0], o[1], o[2], o[3]};
	v_mul_f32_e32 v23, v23, v176
	v_mul_f32_e32 v24, v24, v177
	v_mul_f32_e32 v25, v25, v182
	v_add_f32_e32 v10, v10, v122
	v_add_f32_e32 v11, v11, v123
	v_add_f32_e32 v12, v12, v124
	v_add_f32_e32 v13, v13, v125
	v_mul_f32_e32 v10, 0xbfb8aa3b, v10
	v_mul_f32_e32 v11, 0xbfb8aa3b, v11
	v_mul_f32_e32 v12, 0xbfb8aa3b, v12
	v_lshlrev_b32_e32 v2, 16, v0
	v_and_b32_e32 v0, 0xffff0000, v0
	v_lshlrev_b32_e32 v3, 16, v1
	v_and_b32_e32 v1, 0xffff0000, v1
	v_mul_f32_e32 v2, v22, v2
	v_mul_f32_e32 v0, v23, v0
	v_mul_f32_e32 v4, v24, v3
	v_mul_f32_e32 v1, v25, v1
	v_cvt_pk_bf16_f32 v2, v6, v2
	v_cvt_pk_bf16_f32 v3, v7, v0
	v_cvt_pk_bf16_f32 v4, v8, v4
	v_cvt_pk_bf16_f32 v5, v9, v1
	global_store_dwordx4 v[150:151], v[2:5], off offset:32
	v_mov_b32_e32 v0, v228
	v_mov_b32_e32 v1, v229
	v_mul_f32_e32 v13, 0xbfb8aa3b, v13
	v_exp_f32_e32 v10, v10
	v_exp_f32_e32 v11, v11
	v_exp_f32_e32 v12, v12
	v_exp_f32_e32 v13, v13
	v_add_f32_e32 v10, 1.0, v10
	v_add_f32_e32 v11, 1.0, v11
	v_add_f32_e32 v12, 1.0, v12
	v_add_f32_e32 v13, 1.0, v13
	v_rcp_f32_e32 v10, v10
	v_rcp_f32_e32 v11, v11
	v_rcp_f32_e32 v12, v12
	v_rcp_f32_e32 v13, v13
	v_mul_f32_e32 v10, v138, v10
	v_mul_f32_e32 v11, v139, v11
	v_mul_f32_e32 v12, v140, v12
	v_mul_f32_e32 v13, v141, v13
	v_mul_f32_e32 v10, 0x3fb8aa3b, v10
	v_mul_f32_e32 v11, 0x3fb8aa3b, v11
	v_mul_f32_e32 v12, 0x3fb8aa3b, v12
	v_mul_f32_e32 v13, 0x3fb8aa3b, v13
	v_add_f32_e32 v26, v26, v130
	v_add_f32_e32 v27, v27, v131
	v_add_f32_e32 v28, v28, v132
	v_add_f32_e32 v29, v29, v133
	v_exp_f32_e32 v10, v10
	v_exp_f32_e32 v11, v11
	v_exp_f32_e32 v12, v12
	v_exp_f32_e32 v13, v13
	v_mul_f32_e32 v26, 0xbfb8aa3b, v26
	v_mul_f32_e32 v27, 0xbfb8aa3b, v27
	v_mul_f32_e32 v28, 0xbfb8aa3b, v28
	v_mul_f32_e32 v29, 0xbfb8aa3b, v29
	v_exp_f32_e32 v26, v26
	v_exp_f32_e32 v27, v27
	v_exp_f32_e32 v28, v28
	v_exp_f32_e32 v29, v29
	v_sub_f32_e32 v10, 1.0, v10
	v_sub_f32_e32 v11, 1.0, v11
	v_sub_f32_e32 v12, 1.0, v12
	v_sub_f32_e32 v13, 1.0, v13
	v_sub_f32_e32 v183, 2.0, v10
	v_sub_f32_e32 v184, 2.0, v11
	v_sub_f32_e32 v185, 2.0, v12
	v_sub_f32_e32 v186, 2.0, v13
	v_add_f32_e32 v26, 1.0, v26
	v_add_f32_e32 v27, 1.0, v27
	v_add_f32_e32 v28, 1.0, v28
	v_add_f32_e32 v29, 1.0, v29
	v_mul_f32_e32 v183, v10, v183
	v_mul_f32_e32 v184, v11, v184
	v_mul_f32_e32 v185, v12, v185
	v_mul_f32_e32 v186, v13, v186
	v_rcp_f32_e32 v26, v26
	v_rcp_f32_e32 v27, v27
	v_rcp_f32_e32 v28, v28
	v_rcp_f32_e32 v29, v29
	v_sqrt_f32_e32 v183, v183
	v_sqrt_f32_e32 v184, v184
	v_sqrt_f32_e32 v185, v185
	v_sqrt_f32_e32 v186, v186
	v_mul_f32_e32 v26, v26, v183
	v_mul_f32_e32 v27, v27, v184
	v_mul_f32_e32 v28, v28, v185
	v_mul_f32_e32 v29, v29, v186
	v_add_f32_e32 v14, v14, v126
	v_add_f32_e32 v15, v15, v127
	v_add_f32_e32 v16, v16, v128
	v_add_f32_e32 v17, v17, v129
	v_mul_f32_e32 v14, 0xbfb8aa3b, v14
	v_mul_f32_e32 v15, 0xbfb8aa3b, v15
	v_mul_f32_e32 v16, 0xbfb8aa3b, v16
	v_mul_f32_e32 v17, 0xbfb8aa3b, v17
	v_exp_f32_e32 v14, v14
	v_exp_f32_e32 v15, v15
	v_exp_f32_e32 v16, v16
	v_exp_f32_e32 v17, v17
	v_add_f32_e32 v14, 1.0, v14
	v_add_f32_e32 v15, 1.0, v15
	v_lshlrev_b32_e32 v2, 16, v0
	v_and_b32_e32 v0, 0xffff0000, v0
	v_lshlrev_b32_e32 v3, 16, v1
	v_and_b32_e32 v1, 0xffff0000, v1
	v_mul_f32_e32 v2, v26, v2
	v_mul_f32_e32 v0, v27, v0
	v_mul_f32_e32 v4, v28, v3
	v_mul_f32_e32 v1, v29, v1
	v_cvt_pk_bf16_f32 v2, v10, v2
	v_cvt_pk_bf16_f32 v3, v11, v0
	v_cvt_pk_bf16_f32 v4, v12, v4
	v_cvt_pk_bf16_f32 v5, v13, v1
	global_store_dwordx4 v[150:151], v[2:5], off offset:64
	v_mov_b32_e32 v0, v230
	v_mov_b32_e32 v1, v231
	v_add_f32_e32 v16, 1.0, v16
	v_add_f32_e32 v17, 1.0, v17
	v_rcp_f32_e32 v14, v14
	v_rcp_f32_e32 v15, v15
	v_rcp_f32_e32 v16, v16
	v_rcp_f32_e32 v17, v17
	v_mul_f32_e32 v14, v142, v14
	v_mul_f32_e32 v15, v143, v15
	v_mul_f32_e32 v16, v144, v16
	v_mul_f32_e32 v17, v145, v17
	v_mul_f32_e32 v14, 0x3fb8aa3b, v14
	v_mul_f32_e32 v15, 0x3fb8aa3b, v15
	v_mul_f32_e32 v16, 0x3fb8aa3b, v16
	v_mul_f32_e32 v17, 0x3fb8aa3b, v17
	v_add_f32_e32 v30, v30, v134
	v_add_f32_e32 v31, v31, v135
	v_add_f32_e32 v32, v32, v136
	v_add_f32_e32 v33, v33, v137
	v_exp_f32_e32 v14, v14
	v_exp_f32_e32 v15, v15
	v_exp_f32_e32 v16, v16
	v_exp_f32_e32 v17, v17
	v_mul_f32_e32 v30, 0xbfb8aa3b, v30
	v_mul_f32_e32 v31, 0xbfb8aa3b, v31
	v_mul_f32_e32 v32, 0xbfb8aa3b, v32
	v_mul_f32_e32 v33, 0xbfb8aa3b, v33
	v_exp_f32_e32 v30, v30
	v_exp_f32_e32 v31, v31
	v_exp_f32_e32 v32, v32
	v_exp_f32_e32 v33, v33
	v_sub_f32_e32 v14, 1.0, v14
	v_sub_f32_e32 v15, 1.0, v15
	v_sub_f32_e32 v16, 1.0, v16
	v_sub_f32_e32 v17, 1.0, v17
	v_sub_f32_e32 v187, 2.0, v14
	v_sub_f32_e32 v188, 2.0, v15
	v_sub_f32_e32 v189, 2.0, v16
	v_sub_f32_e32 v190, 2.0, v17
	v_add_f32_e32 v30, 1.0, v30
	v_add_f32_e32 v31, 1.0, v31
	v_add_f32_e32 v32, 1.0, v32
	v_add_f32_e32 v33, 1.0, v33
	v_mul_f32_e32 v187, v14, v187
	v_mul_f32_e32 v188, v15, v188
	v_mul_f32_e32 v189, v16, v189
	v_mul_f32_e32 v190, v17, v190
	v_rcp_f32_e32 v30, v30
	v_rcp_f32_e32 v31, v31
	v_rcp_f32_e32 v32, v32
	v_rcp_f32_e32 v33, v33
	v_sqrt_f32_e32 v187, v187
	v_sqrt_f32_e32 v188, v188
	v_sqrt_f32_e32 v189, v189
	v_sqrt_f32_e32 v190, v190
	v_mul_f32_e32 v30, v30, v187
	v_mul_f32_e32 v31, v31, v188
	v_mul_f32_e32 v32, v32, v189
	v_mul_f32_e32 v33, v33, v190
	v_lshlrev_b32_e32 v2, 16, v0
	v_and_b32_e32 v0, 0xffff0000, v0
	v_lshlrev_b32_e32 v3, 16, v1
	v_and_b32_e32 v1, 0xffff0000, v1
	v_mul_f32_e32 v2, v30, v2
	v_mul_f32_e32 v0, v31, v0
	v_mul_f32_e32 v4, v32, v3
	v_mul_f32_e32 v1, v33, v1
	v_cvt_pk_bf16_f32 v2, v14, v2
	v_cvt_pk_bf16_f32 v3, v15, v0
	v_cvt_pk_bf16_f32 v4, v16, v4
	v_cvt_pk_bf16_f32 v5, v17, v1
	global_store_dwordx4 v[150:151], v[2:5], off offset:96
	s_waitcnt vmcnt(15)
; DI unsigned pk2(float lo, float hi) { f32x2_t v = {lo, hi}; bf16x2_t b = __builtin_convertvector(v, bf16x2_t); return __builtin_bit_cast(unsigned, b); }
; DI float bflo(unsigned u) { return __uint_as_float(u << 16); }
; DI float bfhi(unsigned u) { return __uint_as_float(u & 0xffff0000u); }
; DI float sigm(float x) { return __builtin_amdgcn_rcpf(1.f + __builtin_amdgcn_exp2f(-1.4426950408889634f * x)); }
; __global__ void __launch_bounds__(512, 2) fwd_kernel(Args args) {
;     ...
;             for (int i = 0; i < 4; ++i) {
;                 const size_t tok = (size_t)pm * 256 + ((wave >> 2) + 2 * i) * 32 + c;
;                 bf16x8 xf[8];
; #pragma unroll
;                 for (int ks = 0; ks < 8; ++ks) xf[ks] = *(const bf16x8*)(xcb + tok * DM + 128 * h + 16 * ks + 8 * hi2);
;                 f32x16 ar, ai;
; #pragma unroll
;                 for (int r = 0; r < 16; ++r) { ar[r] = 0.f; ai[r] = 0.f; }
; #pragma unroll
;                 for (int ks = 0; ks < 8; ++ks) {
;                     ar = __builtin_amdgcn_mfma_f32_32x32x16_bf16(wrf[ks], xf[ks], ar, 0, 0, 0);
;                     ai = __builtin_amdgcn_mfma_f32_32x32x16_bf16(wif[ks], xf[ks], ai, 0, 0, 0);
;                 }
; #pragma unroll
;                 for (int g = 0; g < 4; ++g) {
;                     const int ch = 128 * h + 32 * cb + 8 * g + 4 * hi2;
;                     const u32x2 xv = *(const u32x2*)(xcb + tok * DM + ch);
;                     const float xx[4] = {bflo(xv.x), bfhi(xv.x), bflo(xv.y), bfhi(xv.y)};
;                     unsigned o[4];
; #pragma unroll
;                     for (int e = 0; e < 4; ++e) { const float r = sigm(ar[4 * g + e] + br[g][e]), ig = sigm(ai[4 * g + e] + bi[g][e]);
;                         const float oma = 1.f - __expf(r * sp[g][e]);
;                         o[e] = pk2(oma, __builtin_amdgcn_sqrtf(oma * (2.f - oma)) * ig * xx[e]); }
;                     *(u32x4*)(AU + tok * DM + ch) = (u32x4){o[0], o[1], o[2], o[3]};
	v_mfma_f32_32x32x16_bf16 v[2:17], v[34:37], v[192:195], 0
	v_mfma_f32_32x32x16_bf16 v[18:33], v[42:45], v[192:195], 0
	s_waitcnt vmcnt(14)
	v_mfma_f32_32x32x16_bf16 v[2:17], v[38:41], v[196:199], v[2:17]
	v_mfma_f32_32x32x16_bf16 v[18:33], v[46:49], v[196:199], v[18:33]
	s_waitcnt vmcnt(13)
	v_mfma_f32_32x32x16_bf16 v[2:17], v[50:53], v[200:203], v[2:17]
	v_mfma_f32_32x32x16_bf16 v[18:33], v[58:61], v[200:203], v[18:33]
	s_waitcnt vmcnt(12)
	v_mfma_f32_32x32x16_bf16 v[2:17], v[54:57], v[204:207], v[2:17]
	v_mfma_f32_32x32x16_bf16 v[18:33], v[62:65], v[204:207], v[18:33]
	s_waitcnt vmcnt(11)
	v_mfma_f32_32x32x16_bf16 v[2:17], v[66:69], v[208:211], v[2:17]
	v_mfma_f32_32x32x16_bf16 v[18:33], v[74:77], v[208:211], v[18:33]
	v_lshl_add_u64 v[150:151], s[96:97], 0, v[162:163]
	v_lshl_add_u64 v[152:153], s[96:97], 0, v[160:161]
	v_lshl_add_u64 v[160:161], v[160:161], 0, s[6:7]
	v_lshl_add_u64 v[162:163], v[162:163], 0, s[8:9]
	s_waitcnt vmcnt(10)
	v_mfma_f32_32x32x16_bf16 v[2:17], v[70:73], v[212:215], v[2:17]
	v_mfma_f32_32x32x16_bf16 v[18:33], v[78:81], v[212:215], v[18:33]
	v_add_co_u32_e32 v148, vcc, s13, v150
	s_nop 1
	v_addc_co_u32_e32 v149, vcc, 0, v151, vcc
	v_add_co_u32_e32 v146, vcc, s14, v152
	s_waitcnt vmcnt(9)
	v_mfma_f32_32x32x16_bf16 v[2:17], v[82:85], v[216:219], v[2:17]
	s_nop 0
	v_addc_co_u32_e32 v147, vcc, 0, v153, vcc
	s_waitcnt vmcnt(4)
	v_mov_b32_e32 v0, v232
	v_mov_b32_e32 v1, v233
	v_lshlrev_b32_e32 v150, 16, v0
	s_waitcnt vmcnt(8)
	v_mfma_f32_32x32x16_bf16 v[2:17], v[86:89], v[220:223], v[2:17]
	v_and_b32_e32 v0, 0xffff0000, v0
	v_lshlrev_b32_e32 v151, 16, v1
	v_and_b32_e32 v1, 0xffff0000, v1
	v_mfma_f32_32x32x16_bf16 v[18:33], v[90:93], v[216:219], v[18:33]
	s_nop 7
	v_add_f32_e32 v2, v2, v98
	v_add_f32_e32 v3, v3, v99
	v_add_f32_e32 v4, v4, v100
	v_add_f32_e32 v5, v5, v101
	v_mul_f32_e32 v2, 0xbfb8aa3b, v2
	v_mul_f32_e32 v3, 0xbfb8aa3b, v3
	v_mul_f32_e32 v4, 0xbfb8aa3b, v4
	v_mul_f32_e32 v5, 0xbfb8aa3b, v5
	v_exp_f32_e32 v2, v2
	v_exp_f32_e32 v3, v3
	v_exp_f32_e32 v4, v4
	v_exp_f32_e32 v5, v5
	v_mfma_f32_32x32x16_bf16 v[18:33], v[94:97], v[220:223], v[18:33]
	v_add_f32_e32 v2, 1.0, v2
	v_add_f32_e32 v3, 1.0, v3
	v_add_f32_e32 v4, 1.0, v4
	v_add_f32_e32 v5, 1.0, v5
	v_rcp_f32_e32 v2, v2
	v_rcp_f32_e32 v3, v3
	v_rcp_f32_e32 v4, v4
	v_rcp_f32_e32 v5, v5
	v_mul_f32_e32 v2, v114, v2
	v_mul_f32_e32 v3, v115, v3
	v_mul_f32_e32 v4, v116, v4
	v_mul_f32_e32 v5, v117, v5
	v_mul_f32_e32 v2, 0x3fb8aa3b, v2
	v_mul_f32_e32 v3, 0x3fb8aa3b, v3
	v_mul_f32_e32 v4, 0x3fb8aa3b, v4
	v_mul_f32_e32 v5, 0x3fb8aa3b, v5
	v_add_f32_e32 v18, v18, v106
	v_add_f32_e32 v19, v19, v107
	v_add_f32_e32 v20, v20, v108
	v_add_f32_e32 v21, v21, v109
	v_exp_f32_e32 v2, v2
	v_exp_f32_e32 v3, v3
	v_exp_f32_e32 v4, v4
	v_exp_f32_e32 v5, v5
	v_mul_f32_e32 v18, 0xbfb8aa3b, v18
	v_mul_f32_e32 v19, 0xbfb8aa3b, v19
	v_mul_f32_e32 v20, 0xbfb8aa3b, v20
	v_mul_f32_e32 v21, 0xbfb8aa3b, v21
	v_exp_f32_e32 v18, v18
	v_exp_f32_e32 v19, v19
	v_exp_f32_e32 v20, v20
	v_exp_f32_e32 v21, v21
	v_sub_f32_e32 v2, 1.0, v2
	v_sub_f32_e32 v3, 1.0, v3
	v_sub_f32_e32 v4, 1.0, v4
	v_sub_f32_e32 v5, 1.0, v5
	v_sub_f32_e32 v152, 2.0, v2
	v_sub_f32_e32 v153, 2.0, v3
	v_sub_f32_e32 v154, 2.0, v4
	v_sub_f32_e32 v172, 2.0, v5
	v_add_f32_e32 v18, 1.0, v18
	v_add_f32_e32 v19, 1.0, v19
	v_add_f32_e32 v20, 1.0, v20
	v_add_f32_e32 v21, 1.0, v21
	v_mul_f32_e32 v152, v2, v152
	v_mul_f32_e32 v153, v3, v153
	v_mul_f32_e32 v154, v4, v154
	v_mul_f32_e32 v172, v5, v172
	v_rcp_f32_e32 v18, v18
	v_rcp_f32_e32 v19, v19
	v_rcp_f32_e32 v20, v20
	v_rcp_f32_e32 v21, v21
	v_sqrt_f32_e32 v152, v152
	v_sqrt_f32_e32 v153, v153
	v_sqrt_f32_e32 v154, v154
	v_sqrt_f32_e32 v172, v172
	v_mul_f32_e32 v18, v18, v152
	v_mul_f32_e32 v19, v19, v153
	v_mul_f32_e32 v20, v20, v154
	v_mul_f32_e32 v21, v21, v172
	v_mul_f32_e32 v18, v18, v150
	v_mul_f32_e32 v0, v19, v0
	v_mul_f32_e32 v19, v20, v151
	v_mul_f32_e32 v1, v21, v1
	v_cvt_pk_bf16_f32 v2, v2, v18
	v_cvt_pk_bf16_f32 v3, v3, v0
	v_cvt_pk_bf16_f32 v4, v4, v19
	v_cvt_pk_bf16_f32 v5, v5, v1
	global_store_dwordx4 v[146:147], v[2:5], off
	v_mov_b32_e32 v0, v234
	v_mov_b32_e32 v1, v235
	v_add_f32_e32 v6, v6, v102
	v_add_f32_e32 v7, v7, v103
	v_add_f32_e32 v8, v8, v104
	v_add_f32_e32 v9, v9, v105
	v_mul_f32_e32 v6, 0xbfb8aa3b, v6
	v_mul_f32_e32 v7, 0xbfb8aa3b, v7
	v_mul_f32_e32 v8, 0xbfb8aa3b, v8
	v_mul_f32_e32 v9, 0xbfb8aa3b, v9
	v_exp_f32_e32 v6, v6
	v_exp_f32_e32 v7, v7
	v_exp_f32_e32 v2, v8
	v_exp_f32_e32 v4, v9
	v_add_f32_e32 v6, 1.0, v6
	v_add_f32_e32 v7, 1.0, v7
	v_add_f32_e32 v2, 1.0, v2
	v_add_f32_e32 v4, 1.0, v4
	v_rcp_f32_e32 v6, v6
	v_rcp_f32_e32 v7, v7
	v_rcp_f32_e32 v2, v2
	v_rcp_f32_e32 v4, v4
	v_mul_f32_e32 v6, v118, v6
	v_mul_f32_e32 v7, v119, v7
	v_mul_f32_e32 v2, v120, v2
	v_mul_f32_e32 v4, v121, v4
	v_mul_f32_e32 v6, 0x3fb8aa3b, v6
	v_mul_f32_e32 v7, 0x3fb8aa3b, v7
	v_mul_f32_e32 v2, 0x3fb8aa3b, v2
	v_mul_f32_e32 v4, 0x3fb8aa3b, v4
	v_add_f32_e32 v22, v22, v110
	v_add_f32_e32 v23, v23, v111
	v_add_f32_e32 v24, v24, v112
	v_add_f32_e32 v25, v25, v113
	v_exp_f32_e32 v6, v6
	v_exp_f32_e32 v7, v7
	v_exp_f32_e32 v2, v2
	v_exp_f32_e32 v4, v4
	v_mul_f32_e32 v22, 0xbfb8aa3b, v22
	v_mul_f32_e32 v23, 0xbfb8aa3b, v23
	v_mul_f32_e32 v24, 0xbfb8aa3b, v24
	v_mul_f32_e32 v25, 0xbfb8aa3b, v25
	v_exp_f32_e32 v22, v22
	v_exp_f32_e32 v23, v23
	v_exp_f32_e32 v3, v24
	v_exp_f32_e32 v5, v25
	v_sub_f32_e32 v6, 1.0, v6
	v_sub_f32_e32 v7, 1.0, v7
	v_sub_f32_e32 v18, 1.0, v2
	v_sub_f32_e32 v19, 1.0, v4
	v_sub_f32_e32 v2, 2.0, v6
	v_sub_f32_e32 v4, 2.0, v7
	v_sub_f32_e32 v20, 2.0, v18
	v_sub_f32_e32 v21, 2.0, v19
	v_add_f32_e32 v8, 1.0, v22
	v_add_f32_e32 v9, 1.0, v23
; DI unsigned pk2(float lo, float hi) { f32x2_t v = {lo, hi}; bf16x2_t b = __builtin_convertvector(v, bf16x2_t); return __builtin_bit_cast(unsigned, b); }
; DI float bflo(unsigned u) { return __uint_as_float(u << 16); }
; DI float bfhi(unsigned u) { return __uint_as_float(u & 0xffff0000u); }
; DI float sigm(float x) { return __builtin_amdgcn_rcpf(1.f + __builtin_amdgcn_exp2f(-1.4426950408889634f * x)); }
; __global__ void __launch_bounds__(512, 2) fwd_kernel(Args args) {
;     ...
;                 for (int g = 0; g < 4; ++g) {
;                     const int ch = 128 * h + 32 * cb + 8 * g + 4 * hi2;
;                     const u32x2 xv = *(const u32x2*)(xcb + tok * DM + ch);
;                     const float xx[4] = {bflo(xv.x), bfhi(xv.x), bflo(xv.y), bfhi(xv.y)};
;                     unsigned o[4];
; #pragma unroll
;                     for (int e = 0; e < 4; ++e) { const float r = sigm(ar[4 * g + e] + br[g][e]), ig = sigm(ai[4 * g + e] + bi[g][e]);
;                         const float oma = 1.f - __expf(r * sp[g][e]);
;                         o[e] = pk2(oma, __builtin_amdgcn_sqrtf(oma * (2.f - oma)) * ig * xx[e]); }
;                     *(u32x4*)(AU + tok * DM + ch) = (u32x4){o[0], o[1], o[2], o[3]};
;                 }
;             }
;         }
	v_add_f32_e32 v3, 1.0, v3
	v_add_f32_e32 v5, 1.0, v5
	v_mul_f32_e32 v2, v6, v2
	v_mul_f32_e32 v4, v7, v4
	v_mul_f32_e32 v20, v18, v20
	v_mul_f32_e32 v21, v19, v21
	v_rcp_f32_e32 v8, v8
	v_rcp_f32_e32 v9, v9
	v_rcp_f32_e32 v3, v3
	v_rcp_f32_e32 v5, v5
	v_sqrt_f32_e32 v2, v2
	v_sqrt_f32_e32 v4, v4
	v_sqrt_f32_e32 v20, v20
	v_sqrt_f32_e32 v21, v21
	v_mul_f32_e32 v2, v8, v2
	v_mul_f32_e32 v4, v9, v4
	v_mul_f32_e32 v3, v3, v20
	v_mul_f32_e32 v5, v5, v21
	v_add_f32_e32 v10, v10, v122
	v_add_f32_e32 v11, v11, v123
	v_add_f32_e32 v12, v12, v124
	v_add_f32_e32 v13, v13, v125
	v_mul_f32_e32 v10, 0xbfb8aa3b, v10
	v_mul_f32_e32 v11, 0xbfb8aa3b, v11
	v_add_f32_e32 v26, v26, v130
	v_lshlrev_b32_e32 v8, 16, v0
	v_and_b32_e32 v0, 0xffff0000, v0
	v_lshlrev_b32_e32 v9, 16, v1
	v_and_b32_e32 v1, 0xffff0000, v1
	v_mul_f32_e32 v2, v2, v8
	v_mul_f32_e32 v0, v4, v0
	v_mul_f32_e32 v4, v3, v9
	v_mul_f32_e32 v1, v5, v1
	v_cvt_pk_bf16_f32 v2, v6, v2
	v_cvt_pk_bf16_f32 v3, v7, v0
	v_cvt_pk_bf16_f32 v4, v18, v4
	v_cvt_pk_bf16_f32 v5, v19, v1
	global_store_dwordx4 v[146:147], v[2:5], off offset:32
	v_mov_b32_e32 v0, v236
	v_mov_b32_e32 v1, v237
	v_exp_f32_e32 v7, v10
	v_mul_f32_e32 v3, 0xbfb8aa3b, v12
	v_mul_f32_e32 v5, 0xbfb8aa3b, v13
	v_exp_f32_e32 v9, v11
	v_exp_f32_e32 v3, v3
	v_exp_f32_e32 v5, v5
	v_add_f32_e32 v7, 1.0, v7
	v_add_f32_e32 v9, 1.0, v9
	v_add_f32_e32 v3, 1.0, v3
	v_add_f32_e32 v5, 1.0, v5
	v_rcp_f32_e32 v7, v7
	v_rcp_f32_e32 v9, v9
	v_rcp_f32_e32 v3, v3
	v_rcp_f32_e32 v5, v5
	v_mul_f32_e32 v7, v138, v7
	v_mul_f32_e32 v9, v139, v9
	v_mul_f32_e32 v3, v140, v3
	v_mul_f32_e32 v5, v141, v5
	v_mul_f32_e32 v7, 0x3fb8aa3b, v7
	v_mul_f32_e32 v9, 0x3fb8aa3b, v9
	v_mul_f32_e32 v3, 0x3fb8aa3b, v3
	v_mul_f32_e32 v5, 0x3fb8aa3b, v5
	v_add_f32_e32 v27, v27, v131
	v_add_f32_e32 v28, v28, v132
	v_add_f32_e32 v29, v29, v133
	v_exp_f32_e32 v7, v7
	v_exp_f32_e32 v9, v9
	v_exp_f32_e32 v3, v3
	v_exp_f32_e32 v5, v5
	v_mul_f32_e32 v26, 0xbfb8aa3b, v26
	v_mul_f32_e32 v2, 0xbfb8aa3b, v27
	v_mul_f32_e32 v4, 0xbfb8aa3b, v28
	v_mul_f32_e32 v6, 0xbfb8aa3b, v29
	v_exp_f32_e32 v8, v26
	v_exp_f32_e32 v2, v2
	v_exp_f32_e32 v4, v4
	v_exp_f32_e32 v6, v6
	v_sub_f32_e32 v7, 1.0, v7
	v_sub_f32_e32 v9, 1.0, v9
	v_sub_f32_e32 v10, 1.0, v3
	v_sub_f32_e32 v5, 1.0, v5
	v_sub_f32_e32 v3, 2.0, v7
	v_sub_f32_e32 v11, 2.0, v9
	v_sub_f32_e32 v12, 2.0, v10
	v_sub_f32_e32 v13, 2.0, v5
	v_add_f32_e32 v8, 1.0, v8
	v_add_f32_e32 v2, 1.0, v2
	v_add_f32_e32 v4, 1.0, v4
	v_add_f32_e32 v6, 1.0, v6
	v_mul_f32_e32 v3, v7, v3
	v_mul_f32_e32 v11, v9, v11
	v_mul_f32_e32 v12, v10, v12
	v_mul_f32_e32 v13, v5, v13
	v_rcp_f32_e32 v8, v8
	v_rcp_f32_e32 v2, v2
	v_rcp_f32_e32 v4, v4
	v_rcp_f32_e32 v6, v6
	v_sqrt_f32_e32 v3, v3
	v_sqrt_f32_e32 v11, v11
	v_sqrt_f32_e32 v12, v12
	v_sqrt_f32_e32 v13, v13
	v_mul_f32_e32 v3, v8, v3
	v_mul_f32_e32 v2, v2, v11
	v_mul_f32_e32 v4, v4, v12
	v_mul_f32_e32 v6, v6, v13
	v_add_f32_e32 v14, v14, v126
	v_add_f32_e32 v30, v30, v134
	v_lshlrev_b32_e32 v8, 16, v0
	v_and_b32_e32 v0, 0xffff0000, v0
	v_lshlrev_b32_e32 v11, 16, v1
	v_and_b32_e32 v1, 0xffff0000, v1
	v_mul_f32_e32 v3, v3, v8
	v_mul_f32_e32 v0, v2, v0
	v_mul_f32_e32 v4, v4, v11
	v_mul_f32_e32 v1, v6, v1
	v_cvt_pk_bf16_f32 v2, v7, v3
	v_cvt_pk_bf16_f32 v3, v9, v0
	v_cvt_pk_bf16_f32 v4, v10, v4
	v_cvt_pk_bf16_f32 v5, v5, v1
	global_store_dwordx4 v[146:147], v[2:5], off offset:64
	v_mov_b32_e32 v0, v238
	v_mov_b32_e32 v1, v239
	v_add_f32_e32 v6, v17, v129
	v_add_f32_e32 v2, v15, v127
	v_add_f32_e32 v4, v16, v128
	v_mul_f32_e32 v8, 0xbfb8aa3b, v14
	v_mul_f32_e32 v2, 0xbfb8aa3b, v2
	v_mul_f32_e32 v4, 0xbfb8aa3b, v4
	v_mul_f32_e32 v6, 0xbfb8aa3b, v6
	v_exp_f32_e32 v8, v8
	v_exp_f32_e32 v2, v2
	v_exp_f32_e32 v4, v4
	v_exp_f32_e32 v6, v6
	v_add_f32_e32 v8, 1.0, v8
	v_add_f32_e32 v2, 1.0, v2
	v_add_f32_e32 v4, 1.0, v4
	v_add_f32_e32 v6, 1.0, v6
	v_rcp_f32_e32 v8, v8
	v_rcp_f32_e32 v2, v2
	v_rcp_f32_e32 v4, v4
	v_rcp_f32_e32 v6, v6
	v_mul_f32_e32 v8, v142, v8
	v_mul_f32_e32 v2, v143, v2
	v_mul_f32_e32 v4, v144, v4
	v_mul_f32_e32 v6, v145, v6
	v_mul_f32_e32 v8, 0x3fb8aa3b, v8
	v_mul_f32_e32 v2, 0x3fb8aa3b, v2
	v_mul_f32_e32 v4, 0x3fb8aa3b, v4
	v_mul_f32_e32 v6, 0x3fb8aa3b, v6
	v_add_f32_e32 v3, v31, v135
	v_add_f32_e32 v5, v32, v136
	v_add_f32_e32 v7, v33, v137
	v_exp_f32_e32 v8, v8
	v_exp_f32_e32 v2, v2
	v_exp_f32_e32 v4, v4
	v_exp_f32_e32 v6, v6
	v_mul_f32_e32 v9, 0xbfb8aa3b, v30
	v_mul_f32_e32 v3, 0xbfb8aa3b, v3
	v_mul_f32_e32 v5, 0xbfb8aa3b, v5
	v_mul_f32_e32 v7, 0xbfb8aa3b, v7
	v_exp_f32_e32 v9, v9
	v_exp_f32_e32 v3, v3
	v_exp_f32_e32 v5, v5
	v_exp_f32_e32 v7, v7
	v_sub_f32_e32 v8, 1.0, v8
	v_sub_f32_e32 v10, 1.0, v2
	v_sub_f32_e32 v4, 1.0, v4
	v_sub_f32_e32 v6, 1.0, v6
	v_sub_f32_e32 v2, 2.0, v8
	v_sub_f32_e32 v11, 2.0, v10
	v_sub_f32_e32 v12, 2.0, v4
	v_sub_f32_e32 v13, 2.0, v6
	v_add_f32_e32 v9, 1.0, v9
	v_add_f32_e32 v3, 1.0, v3
	v_add_f32_e32 v5, 1.0, v5
	v_add_f32_e32 v7, 1.0, v7
	v_mul_f32_e32 v2, v8, v2
	v_mul_f32_e32 v11, v10, v11
	v_mul_f32_e32 v12, v4, v12
	v_mul_f32_e32 v13, v6, v13
	v_rcp_f32_e32 v9, v9
	v_rcp_f32_e32 v3, v3
	v_rcp_f32_e32 v5, v5
	v_rcp_f32_e32 v7, v7
	v_sqrt_f32_e32 v2, v2
	v_sqrt_f32_e32 v11, v11
	v_sqrt_f32_e32 v12, v12
	v_sqrt_f32_e32 v13, v13
	v_mul_f32_e32 v2, v9, v2
	v_mul_f32_e32 v3, v3, v11
	v_mul_f32_e32 v5, v5, v12
	v_mul_f32_e32 v7, v7, v13
	v_lshlrev_b32_e32 v9, 16, v0
	v_and_b32_e32 v0, 0xffff0000, v0
	v_lshlrev_b32_e32 v11, 16, v1
	v_and_b32_e32 v1, 0xffff0000, v1
	v_mul_f32_e32 v2, v2, v9
	v_mul_f32_e32 v0, v3, v0
	v_mul_f32_e32 v5, v5, v11
	v_mul_f32_e32 v1, v7, v1
	v_cvt_pk_bf16_f32 v2, v8, v2
	v_cvt_pk_bf16_f32 v3, v10, v0
	v_cvt_pk_bf16_f32 v4, v4, v5
	v_cvt_pk_bf16_f32 v5, v6, v1
	global_store_dwordx4 v[146:147], v[2:5], off offset:96
	s_cbranch_scc0 .LBB0_594
	s_add_i32 s15, s15, s90
	s_add_i32 s10, s10, s11
	s_cmpk_gt_i32 s15, 0x3ff
	s_cbranch_scc0 .LBB0_593
